# v23 plus: grid barrier release in one hop, every workgroup polls the cross-XCD generation and the per-XCD republish (atomic + its completion wait) is gone
# baseline (speedup 1.0000x reference)
; __device__ __forceinline__ unsigned xb_add(unsigned* p, unsigned v) { return __hip_atomic_fetch_add(p, v, __ATOMIC_RELAXED, __HIP_MEMORY_SCOPE_AGENT); }
; __device__ __forceinline__ void xcd_barrier(const XcdBarrier& b) {
;     ...
;             __builtin_amdgcn_fence(__ATOMIC_ACQUIRE, "agent");
;             xb_add(&bar[XB_XGEN(b.x)], 1u);
;             asm volatile("s_waitcnt vmcnt(0)" ::: "memory");
.LBB0_148:
	s_or_b64 exec, exec, s[12:13]
	s_mov_b64 s[12:13], exec
	v_mbcnt_lo_u32_b32 v0, s12, 0
	v_mbcnt_hi_u32_b32 v0, s13, v0
	v_cmp_eq_u32_e32 vcc, 0, v0
	s_waitcnt vmcnt(0)
	buffer_inv sc1
	s_and_saveexec_b64 s[14:15], vcc
	s_cbranch_execz .LBB0_150
	s_bcnt1_i32_b64 s12, s[12:13]
	v_mov_b32_e32 v0, 0x2000
	v_mov_b32_e32 v1, s12
.LBB0_150:
	s_or_b64 exec, exec, s[14:15]
	s_waitcnt vmcnt(0)

; __device__ __forceinline__ unsigned xb_add(unsigned* p, unsigned v) { return __hip_atomic_fetch_add(p, v, __ATOMIC_RELAXED, __HIP_MEMORY_SCOPE_AGENT); }
; __device__ __forceinline__ void xcd_barrier(const XcdBarrier& b) {
;     ...
;             __builtin_amdgcn_fence(__ATOMIC_ACQUIRE, "agent");
;             xb_add(&bar[XB_XGEN(b.x)], 1u);
;             asm volatile("s_waitcnt vmcnt(0)" ::: "memory");
.LBB0_359:
	s_or_b64 exec, exec, s[10:11]
	s_mov_b64 s[10:11], exec
	v_mbcnt_lo_u32_b32 v0, s10, 0
	v_mbcnt_hi_u32_b32 v0, s11, v0
	v_cmp_eq_u32_e32 vcc, 0, v0
	s_waitcnt vmcnt(0)
	buffer_inv sc1
	s_and_saveexec_b64 s[12:13], vcc
	s_cbranch_execz .LBB0_361
	s_bcnt1_i32_b64 s10, s[10:11]
	v_mov_b32_e32 v0, 0x2000
	v_mov_b32_e32 v1, s10
.LBB0_361:
	s_or_b64 exec, exec, s[12:13]
	s_waitcnt vmcnt(0)

; __device__ __forceinline__ unsigned xb_add(unsigned* p, unsigned v) { return __hip_atomic_fetch_add(p, v, __ATOMIC_RELAXED, __HIP_MEMORY_SCOPE_AGENT); }
; __device__ __forceinline__ void xcd_barrier(const XcdBarrier& b) {
;     ...
;             __builtin_amdgcn_fence(__ATOMIC_ACQUIRE, "agent");
;             xb_add(&bar[XB_XGEN(b.x)], 1u);
;             asm volatile("s_waitcnt vmcnt(0)" ::: "memory");
.LBB0_450:
	s_or_b64 exec, exec, s[22:23]
	s_mov_b64 s[22:23], exec
	v_mbcnt_lo_u32_b32 v0, s22, 0
	v_mbcnt_hi_u32_b32 v0, s23, v0
	v_cmp_eq_u32_e32 vcc, 0, v0
	s_waitcnt vmcnt(0)
	buffer_inv sc1
	s_and_saveexec_b64 s[28:29], vcc
	s_cbranch_execz .LBB0_452
	s_bcnt1_i32_b64 s11, s[22:23]
	v_readlane_b32 s12, v247, 11
	v_mov_b32_e32 v0, s11
	v_readlane_b32 s13, v247, 12
	s_nop 4
.LBB0_452:
	s_or_b64 exec, exec, s[28:29]
	s_waitcnt vmcnt(0)

; __device__ __forceinline__ unsigned xb_add(unsigned* p, unsigned v) { return __hip_atomic_fetch_add(p, v, __ATOMIC_RELAXED, __HIP_MEMORY_SCOPE_AGENT); }
; __device__ __forceinline__ void xcd_barrier(const XcdBarrier& b) {
;     ...
;             __builtin_amdgcn_fence(__ATOMIC_ACQUIRE, "agent");
;             xb_add(&bar[XB_XGEN(b.x)], 1u);
;             asm volatile("s_waitcnt vmcnt(0)" ::: "memory");
.LBB0_637:
	s_or_b64 exec, exec, s[22:23]
	s_mov_b64 s[22:23], exec
	v_mbcnt_lo_u32_b32 v0, s22, 0
	v_mbcnt_hi_u32_b32 v0, s23, v0
	v_cmp_eq_u32_e32 vcc, 0, v0
	s_waitcnt vmcnt(0)
	buffer_inv sc1
	s_and_saveexec_b64 s[28:29], vcc
	s_cbranch_execz .LBB0_639
	s_bcnt1_i32_b64 s11, s[22:23]
	v_readlane_b32 s12, v247, 11
	v_mov_b32_e32 v0, s11
	v_readlane_b32 s13, v247, 12
	s_nop 4
.LBB0_639:
	s_or_b64 exec, exec, s[28:29]
	s_waitcnt vmcnt(0)

; __device__ __forceinline__ unsigned xb_add(unsigned* p, unsigned v) { return __hip_atomic_fetch_add(p, v, __ATOMIC_RELAXED, __HIP_MEMORY_SCOPE_AGENT); }
; __device__ __forceinline__ void xcd_barrier(const XcdBarrier& b) {
;     ...
;             __builtin_amdgcn_fence(__ATOMIC_ACQUIRE, "agent");
;             xb_add(&bar[XB_XGEN(b.x)], 1u);
;             asm volatile("s_waitcnt vmcnt(0)" ::: "memory");
.LBB0_727:
	s_or_b64 exec, exec, s[22:23]
	s_mov_b64 s[22:23], exec
	v_mbcnt_lo_u32_b32 v0, s22, 0
	v_mbcnt_hi_u32_b32 v0, s23, v0
	v_cmp_eq_u32_e32 vcc, 0, v0
	s_waitcnt vmcnt(0)
	buffer_inv sc1
	s_and_saveexec_b64 s[28:29], vcc
	s_cbranch_execz .LBB0_729
	s_bcnt1_i32_b64 s11, s[22:23]
	v_readlane_b32 s12, v247, 11
	v_mov_b32_e32 v0, s11
	v_readlane_b32 s13, v247, 12
	s_nop 4
.LBB0_729:
	s_or_b64 exec, exec, s[28:29]
	s_waitcnt vmcnt(0)

; __device__ __forceinline__ unsigned xb_add(unsigned* p, unsigned v) { return __hip_atomic_fetch_add(p, v, __ATOMIC_RELAXED, __HIP_MEMORY_SCOPE_AGENT); }
; __device__ __forceinline__ void xcd_barrier(const XcdBarrier& b) {
;     ...
;             __builtin_amdgcn_fence(__ATOMIC_ACQUIRE, "agent");
;             xb_add(&bar[XB_XGEN(b.x)], 1u);
;             asm volatile("s_waitcnt vmcnt(0)" ::: "memory");
.LBB0_1102:
	s_or_b64 exec, exec, s[22:23]
	s_mov_b64 s[22:23], exec
	v_mbcnt_lo_u32_b32 v0, s22, 0
	v_mbcnt_hi_u32_b32 v0, s23, v0
	v_cmp_eq_u32_e32 vcc, 0, v0
	s_waitcnt vmcnt(0)
	buffer_inv sc1
	s_and_saveexec_b64 s[28:29], vcc
	s_cbranch_execz .LBB0_1104
	s_bcnt1_i32_b64 s11, s[22:23]
	v_readlane_b32 s12, v247, 11
	v_mov_b32_e32 v0, s11
	v_readlane_b32 s13, v247, 12
	s_nop 4
.LBB0_1104:
	s_or_b64 exec, exec, s[28:29]
	s_waitcnt vmcnt(0)

; __device__ __forceinline__ unsigned xb_add(unsigned* p, unsigned v) { return __hip_atomic_fetch_add(p, v, __ATOMIC_RELAXED, __HIP_MEMORY_SCOPE_AGENT); }
; __device__ __forceinline__ void xcd_barrier(const XcdBarrier& b) {
;     ...
;             __builtin_amdgcn_fence(__ATOMIC_ACQUIRE, "agent");
;             xb_add(&bar[XB_XGEN(b.x)], 1u);
;             asm volatile("s_waitcnt vmcnt(0)" ::: "memory");
.LBB0_1167:
	s_or_b64 exec, exec, s[22:23]
	s_mov_b64 s[22:23], exec
	v_mbcnt_lo_u32_b32 v0, s22, 0
	v_mbcnt_hi_u32_b32 v0, s23, v0
	v_cmp_eq_u32_e32 vcc, 0, v0
	s_waitcnt vmcnt(0)
	buffer_inv sc1
	s_and_saveexec_b64 s[28:29], vcc
	s_cbranch_execz .LBB0_1169
	s_bcnt1_i32_b64 s11, s[22:23]
	v_readlane_b32 s12, v247, 11
	v_mov_b32_e32 v0, s11
	v_readlane_b32 s13, v247, 12
	s_nop 4
.LBB0_1169:
	s_or_b64 exec, exec, s[28:29]
	s_waitcnt vmcnt(0)

; __device__ __forceinline__ unsigned xb_add(unsigned* p, unsigned v) { return __hip_atomic_fetch_add(p, v, __ATOMIC_RELAXED, __HIP_MEMORY_SCOPE_AGENT); }
; __device__ __forceinline__ void xcd_barrier(const XcdBarrier& b) {
;     ...
;             __builtin_amdgcn_fence(__ATOMIC_ACQUIRE, "agent");
;             xb_add(&bar[XB_XGEN(b.x)], 1u);
;             asm volatile("s_waitcnt vmcnt(0)" ::: "memory");
.LBB0_1241:
	s_or_b64 exec, exec, s[22:23]
	s_mov_b64 s[22:23], exec
	v_mbcnt_lo_u32_b32 v0, s22, 0
	v_mbcnt_hi_u32_b32 v0, s23, v0
	v_cmp_eq_u32_e32 vcc, 0, v0
	s_waitcnt vmcnt(0)
	buffer_inv sc1
	s_and_saveexec_b64 s[28:29], vcc
	s_cbranch_execz .LBB0_1243
	s_bcnt1_i32_b64 s11, s[22:23]
	v_readlane_b32 s12, v247, 11
	v_mov_b32_e32 v0, s11
	v_readlane_b32 s13, v247, 12
	s_nop 4
.LBB0_1243:
	s_or_b64 exec, exec, s[28:29]
	s_waitcnt vmcnt(0)

; __device__ __forceinline__ unsigned xb_add(unsigned* p, unsigned v) { return __hip_atomic_fetch_add(p, v, __ATOMIC_RELAXED, __HIP_MEMORY_SCOPE_AGENT); }
; __device__ __forceinline__ void xcd_barrier(const XcdBarrier& b) {
;     ...
;             __builtin_amdgcn_fence(__ATOMIC_ACQUIRE, "agent");
;             xb_add(&bar[XB_XGEN(b.x)], 1u);
;             asm volatile("s_waitcnt vmcnt(0)" ::: "memory");
.LBB0_1420:
	s_or_b64 exec, exec, s[22:23]
	s_mov_b64 s[22:23], exec
	v_mbcnt_lo_u32_b32 v0, s22, 0
	v_mbcnt_hi_u32_b32 v0, s23, v0
	v_cmp_eq_u32_e32 vcc, 0, v0
	s_waitcnt vmcnt(0)
	buffer_inv sc1
	s_and_saveexec_b64 s[28:29], vcc
	s_cbranch_execz .LBB0_1422
	s_bcnt1_i32_b64 s6, s[22:23]
	v_readlane_b32 s16, v247, 11
	v_mov_b32_e32 v0, s6
	v_readlane_b32 s17, v247, 12
	s_nop 4
.LBB0_1422:
	s_or_b64 exec, exec, s[28:29]
	s_waitcnt vmcnt(0)

; __device__ __forceinline__ unsigned xb_add(unsigned* p, unsigned v) { return __hip_atomic_fetch_add(p, v, __ATOMIC_RELAXED, __HIP_MEMORY_SCOPE_AGENT); }
; __device__ __forceinline__ void xcd_barrier(const XcdBarrier& b) {
;     ...
;             __builtin_amdgcn_fence(__ATOMIC_ACQUIRE, "agent");
;             xb_add(&bar[XB_XGEN(b.x)], 1u);
;             asm volatile("s_waitcnt vmcnt(0)" ::: "memory");
.LBB0_1572:
	s_or_b64 exec, exec, s[22:23]
	s_mov_b64 s[22:23], exec
	v_mbcnt_lo_u32_b32 v0, s22, 0
	v_mbcnt_hi_u32_b32 v0, s23, v0
	v_cmp_eq_u32_e32 vcc, 0, v0
	s_waitcnt vmcnt(0)
	buffer_inv sc1
	s_and_saveexec_b64 s[28:29], vcc
	s_cbranch_execz .LBB0_1574
	s_bcnt1_i32_b64 s11, s[22:23]
	v_readlane_b32 s12, v247, 11
	v_mov_b32_e32 v0, s11
	v_readlane_b32 s13, v247, 12
	s_nop 4
.LBB0_1574:
	s_or_b64 exec, exec, s[28:29]
	s_waitcnt vmcnt(0)

; __device__ __forceinline__ unsigned xb_add(unsigned* p, unsigned v) { return __hip_atomic_fetch_add(p, v, __ATOMIC_RELAXED, __HIP_MEMORY_SCOPE_AGENT); }
; __device__ __forceinline__ void xcd_barrier(const XcdBarrier& b) {
;     ...
;             __builtin_amdgcn_fence(__ATOMIC_ACQUIRE, "agent");
;             xb_add(&bar[XB_XGEN(b.x)], 1u);
;             asm volatile("s_waitcnt vmcnt(0)" ::: "memory");
.LBB0_1682:
	s_or_b64 exec, exec, s[22:23]
	s_mov_b64 s[22:23], exec
	v_mbcnt_lo_u32_b32 v0, s22, 0
	v_mbcnt_hi_u32_b32 v0, s23, v0
	v_cmp_eq_u32_e32 vcc, 0, v0
	s_waitcnt vmcnt(0)
	buffer_inv sc1
	s_and_saveexec_b64 s[28:29], vcc
	s_cbranch_execz .LBB0_1684
	s_bcnt1_i32_b64 s11, s[22:23]
	v_readlane_b32 s12, v247, 11
	v_mov_b32_e32 v0, s11
	v_readlane_b32 s13, v247, 12
	s_nop 4
.LBB0_1684:
	s_or_b64 exec, exec, s[28:29]
	s_waitcnt vmcnt(0)

; __device__ __forceinline__ unsigned xb_add(unsigned* p, unsigned v) { return __hip_atomic_fetch_add(p, v, __ATOMIC_RELAXED, __HIP_MEMORY_SCOPE_AGENT); }
; __device__ __forceinline__ void xcd_barrier(const XcdBarrier& b) {
;     ...
;             __builtin_amdgcn_fence(__ATOMIC_ACQUIRE, "agent");
;             xb_add(&bar[XB_XGEN(b.x)], 1u);
;             asm volatile("s_waitcnt vmcnt(0)" ::: "memory");
.LBB0_1803:
	s_or_b64 exec, exec, s[22:23]
	s_mov_b64 s[22:23], exec
	v_mbcnt_lo_u32_b32 v0, s22, 0
	v_mbcnt_hi_u32_b32 v0, s23, v0
	v_cmp_eq_u32_e32 vcc, 0, v0
	s_waitcnt vmcnt(0)
	buffer_inv sc1
	s_and_saveexec_b64 s[28:29], vcc
	s_cbranch_execz .LBB0_1805
	s_bcnt1_i32_b64 s11, s[22:23]
	v_readlane_b32 s12, v247, 11
	v_mov_b32_e32 v0, s11
	v_readlane_b32 s13, v247, 12
	s_nop 4
.LBB0_1805:
	s_or_b64 exec, exec, s[28:29]
	s_waitcnt vmcnt(0)

; __device__ __forceinline__ unsigned xb_add(unsigned* p, unsigned v) { return __hip_atomic_fetch_add(p, v, __ATOMIC_RELAXED, __HIP_MEMORY_SCOPE_AGENT); }
; __device__ __forceinline__ void xcd_barrier(const XcdBarrier& b) {
;     ...
;             __builtin_amdgcn_fence(__ATOMIC_ACQUIRE, "agent");
;             xb_add(&bar[XB_XGEN(b.x)], 1u);
;             asm volatile("s_waitcnt vmcnt(0)" ::: "memory");
.LBB0_1866:
	s_or_b64 exec, exec, s[22:23]
	s_mov_b64 s[22:23], exec
	v_mbcnt_lo_u32_b32 v0, s22, 0
	v_mbcnt_hi_u32_b32 v0, s23, v0
	v_cmp_eq_u32_e32 vcc, 0, v0
	s_waitcnt vmcnt(0)
	buffer_inv sc1
	s_and_saveexec_b64 s[28:29], vcc
	s_cbranch_execz .LBB0_1868
	s_bcnt1_i32_b64 s11, s[22:23]
	v_readlane_b32 s12, v247, 11
	v_mov_b32_e32 v0, s11
	v_readlane_b32 s13, v247, 12
	s_nop 4
.LBB0_1868:
	s_or_b64 exec, exec, s[28:29]
	s_waitcnt vmcnt(0)

; __device__ __forceinline__ unsigned xb_add(unsigned* p, unsigned v) { return __hip_atomic_fetch_add(p, v, __ATOMIC_RELAXED, __HIP_MEMORY_SCOPE_AGENT); }
; __device__ __forceinline__ void xcd_barrier(const XcdBarrier& b) {
;     ...
;             __builtin_amdgcn_fence(__ATOMIC_ACQUIRE, "agent");
;             xb_add(&bar[XB_XGEN(b.x)], 1u);
;             asm volatile("s_waitcnt vmcnt(0)" ::: "memory");
.LBB0_2018:
	s_or_b64 exec, exec, s[22:23]
	s_mov_b64 s[22:23], exec
	v_mbcnt_lo_u32_b32 v0, s22, 0
	v_mbcnt_hi_u32_b32 v0, s23, v0
	v_cmp_eq_u32_e32 vcc, 0, v0
	s_waitcnt vmcnt(0)
	buffer_inv sc1
	s_and_saveexec_b64 s[28:29], vcc
	s_cbranch_execz .LBB0_2020
	s_bcnt1_i32_b64 s11, s[22:23]
	v_readlane_b32 s12, v247, 11
	v_mov_b32_e32 v0, s11
	v_readlane_b32 s13, v247, 12
	s_nop 4
.LBB0_2020:
	s_or_b64 exec, exec, s[28:29]
	s_waitcnt vmcnt(0)

; __device__ __forceinline__ unsigned xb_add(unsigned* p, unsigned v) { return __hip_atomic_fetch_add(p, v, __ATOMIC_RELAXED, __HIP_MEMORY_SCOPE_AGENT); }
; __device__ __forceinline__ void xcd_barrier(const XcdBarrier& b) {
;     ...
;             __builtin_amdgcn_fence(__ATOMIC_ACQUIRE, "agent");
;             xb_add(&bar[XB_XGEN(b.x)], 1u);
;             asm volatile("s_waitcnt vmcnt(0)" ::: "memory");
.LBB0_2193:
	s_or_b64 exec, exec, s[22:23]
	s_mov_b64 s[22:23], exec
	v_mbcnt_lo_u32_b32 v0, s22, 0
	v_mbcnt_hi_u32_b32 v0, s23, v0
	v_cmp_eq_u32_e32 vcc, 0, v0
	s_waitcnt vmcnt(0)
	buffer_inv sc1
	s_and_saveexec_b64 s[26:27], vcc
	s_cbranch_execz .LBB0_2195
	s_bcnt1_i32_b64 s6, s[22:23]
	v_readlane_b32 s14, v247, 11
	v_mov_b32_e32 v0, s6
	v_readlane_b32 s15, v247, 12
	s_nop 4
.LBB0_2195:
	s_or_b64 exec, exec, s[26:27]
	s_waitcnt vmcnt(0)

; __device__ __forceinline__ unsigned xb_add(unsigned* p, unsigned v) { return __hip_atomic_fetch_add(p, v, __ATOMIC_RELAXED, __HIP_MEMORY_SCOPE_AGENT); }
; __device__ __forceinline__ void xcd_barrier(const XcdBarrier& b) {
;     ...
;             __builtin_amdgcn_fence(__ATOMIC_ACQUIRE, "agent");
;             xb_add(&bar[XB_XGEN(b.x)], 1u);
;             asm volatile("s_waitcnt vmcnt(0)" ::: "memory");
.LBB0_2289:
	s_or_b64 exec, exec, s[22:23]
	s_mov_b64 s[22:23], exec
	v_mbcnt_lo_u32_b32 v0, s22, 0
	v_mbcnt_hi_u32_b32 v0, s23, v0
	v_cmp_eq_u32_e32 vcc, 0, v0
	s_waitcnt vmcnt(0)
	buffer_inv sc1
	s_and_saveexec_b64 s[36:37], vcc
	s_cbranch_execz .LBB0_2291
	s_bcnt1_i32_b64 s11, s[22:23]
	v_readlane_b32 s14, v247, 11
	v_mov_b32_e32 v0, s11
	v_readlane_b32 s15, v247, 12
	s_nop 4
.LBB0_2291:
	s_or_b64 exec, exec, s[36:37]
	s_waitcnt vmcnt(0)

; __device__ __forceinline__ unsigned xb_add(unsigned* p, unsigned v) { return __hip_atomic_fetch_add(p, v, __ATOMIC_RELAXED, __HIP_MEMORY_SCOPE_AGENT); }
; __device__ __forceinline__ void xcd_barrier(const XcdBarrier& b) {
;     ...
;             __builtin_amdgcn_fence(__ATOMIC_ACQUIRE, "agent");
;             xb_add(&bar[XB_XGEN(b.x)], 1u);
;             asm volatile("s_waitcnt vmcnt(0)" ::: "memory");
.LBB0_2582:
	s_bcnt1_i32_b64 s6, s[22:23]
	v_readlane_b32 s16, v247, 11
	v_mov_b32_e32 v0, s6
	v_readlane_b32 s17, v247, 12
	s_nop 4
	s_getpc_b64 s[98:99]

; __device__ __forceinline__ unsigned xb_add(unsigned* p, unsigned v) { return __hip_atomic_fetch_add(p, v, __ATOMIC_RELAXED, __HIP_MEMORY_SCOPE_AGENT); }
; __device__ __forceinline__ void xcd_barrier(const XcdBarrier& b) {
;     ...
;             __builtin_amdgcn_fence(__ATOMIC_ACQUIRE, "agent");
;             xb_add(&bar[XB_XGEN(b.x)], 1u);
;             asm volatile("s_waitcnt vmcnt(0)" ::: "memory");
.LBB0_2649:
	s_or_b64 exec, exec, s[2:3]
	s_mov_b64 s[2:3], exec
	v_mbcnt_lo_u32_b32 v0, s2, 0
	v_mbcnt_hi_u32_b32 v0, s3, v0
	v_cmp_eq_u32_e32 vcc, 0, v0
	s_waitcnt vmcnt(0)
	buffer_inv sc1
	s_and_saveexec_b64 s[4:5], vcc
	s_cbranch_execz .LBB0_2651
	s_bcnt1_i32_b64 s2, s[2:3]
	v_mov_b32_e32 v1, s2
	v_readlane_b32 s2, v247, 11
	v_mov_b32_e32 v0, 0
	v_readlane_b32 s3, v247, 12
	s_nop 4
.LBB0_2651:
	s_or_b64 exec, exec, s[4:5]
	s_waitcnt vmcnt(0)
